# v11 + NSA sel/win loops: r=1 bias lookups issued as one batch (4 LDS reads in flight instead of 3 dependent round trips)
# speedup vs baseline: 1.0008x; 1.0008x over previous
; template <int MODE>
; __device__ __forceinline__ void nsa_compute(int cur, int buf, int t, int hl, u64 mymask, const bf16x8 (&Qf)[2][2], f32x4 (&O)[4][2], float (&m)[2], float (&l)[2],
;                                             const float (&inv)[2], float* impw, char* lds) {
;     ...
;       for (int kk = 0; kk < 2; ++kk)
; #pragma unroll
;         for (int e = 0; e < 4; ++e) {
;           const int off = 32 * s2 + 16 * kk + e;
;           int idx;
;           if (MODE <= 1) { idx = base - 16 * off; idx = idx > 0 ? idx : 0; } else idx = base - off;
;           sv[kk][e] = S[kk][r][e] * (0.125f * LOG2E) + tb[r * TS + idx];
;         }
;       float pv[2][4];
;       if (MODE == 1) {
; #pragma unroll
;         for (int kk = 0; kk < 2; ++kk)
; #pragma unroll
;           for (int e = 0; e < 4; ++e) pv[kk][e] = __builtin_amdgcn_exp2f(sv[kk][e] - m[r]) * inv[r];
; #pragma unroll
;         for (int kk = 0; kk < 2; ++kk) { g1s[kk] += pv[kk][0] + pv[kk][1] + pv[kk][2] + 0.5f * pv[kk][3]; p3s[kk] += 0.5f * pv[kk][3]; }
;       } else {
;         const float mxa = fmaxf(fmaxf(sv[0][0], sv[0][1]), sv[0][2]), mxb = fmaxf(fmaxf(sv[0][3], sv[1][0]), sv[1][1]);
;         float mx = fmaxf(fmaxf(fmaxf(sv[1][2], sv[1][3]), mxa), mxb);
;         if (MODE == 2) mx = selok ? mx : -__builtin_inff();
;         if (__any(mx > m[r] + 8.0f)) {
;           mx = fmaxf(mx, __shfl_xor(mx, 16)); mx = fmaxf(mx, __shfl_xor(mx, 32));
;           const float mn = fmaxf(m[r], mx), al = __builtin_amdgcn_exp2f(m[r] - mn);
;           m[r] = mn; l[r] *= al;
;           if (MODE != 0) {
; #pragma unroll
;             for (int df = 0; df < 4; ++df) O[df][r] *= al;
;           }
;         }
;         const float me = (MODE == 2) ? (selok ? m[r] : __builtin_inff()) : m[r];
;         float ps = 0.f;
; #pragma unroll
;         for (int kk = 0; kk < 2; ++kk)
; #pragma unroll
;           for (int e = 0; e < 4; ++e) { pv[kk][e] = __builtin_amdgcn_exp2f(sv[kk][e] - me); ps += pv[kk][e]; }
;         l[r] += ps;
.LBB0_364:
	v_sub_f32_e32 v85, v94, v88
	v_exp_f32_e32 v85, v85
	v_sub_f32_e32 v86, v86, v88
	v_exp_f32_e32 v86, v86
	v_sub_f32_e32 v87, v87, v88
	v_exp_f32_e32 v87, v87
	v_sub_f32_e32 v84, v84, v88
	v_exp_f32_e32 v84, v84
	v_add_f32_e32 v89, 0, v85
	v_add_f32_e32 v89, v86, v89
	v_add_f32_e32 v89, v87, v89
	v_sub_f32_e32 v81, v81, v88
	v_add_f32_e32 v94, v84, v89
	v_exp_f32_e32 v89, v81
	v_sub_f32_e32 v80, v80, v88
	v_add_f32_e32 v81, v89, v94
	v_exp_f32_e32 v94, v80
	s_nop 0
	v_add_f32_e32 v80, v94, v81
	v_sub_f32_e32 v81, v83, v88
	v_exp_f32_e32 v95, v81
	v_sub_f32_e32 v81, v82, v88
	v_exp_f32_e32 v88, v81
	v_add_f32_e32 v80, v95, v80
	v_add_f32_e32 v80, v88, v80
	v_add_f32_e32 v190, v190, v80
	v_add_u32_e32 v80, 0xafc, v136
	ds_read2_b32 v[80:81], v80 offset1:1
	v_add_u32_e32 v82, 0xaf4, v136
	ds_read2_b32 v[82:83], v82 offset1:1
	v_add_u32_e32 v222, 0xabc, v136
	ds_read2_b32 v[222:223], v222 offset1:1
	v_add_u32_e32 v230, 0xab4, v136
	ds_read2_b32 v[230:231], v230 offset1:1
	s_waitcnt lgkmcnt(3)
	v_fmamk_f32 v81, v76, 0x3e38aa3b, v81
	v_fmac_f32_e32 v80, 0x3e38aa3b, v77
	s_waitcnt lgkmcnt(2)
	v_fmamk_f32 v78, v78, 0x3e38aa3b, v83
	v_fmac_f32_e32 v82, 0x3e38aa3b, v79
	s_waitcnt lgkmcnt(1)
	v_fmamk_f32 v77, v72, 0x3e38aa3b, v223
	v_fmamk_f32 v76, v73, 0x3e38aa3b, v222
	s_waitcnt lgkmcnt(0)
	v_fmamk_f32 v73, v74, 0x3e38aa3b, v231
	v_fmamk_f32 v72, v75, 0x3e38aa3b, v230
	v_max3_f32 v74, v81, v80, v78
	v_max3_f32 v75, v82, v77, v76
	v_max_f32_e32 v79, v73, v72
	v_max3_f32 v74, v79, v74, v75
	v_add_f32_e32 v75, 0x41000000, v193
	v_cmp_gt_f32_e32 vcc, v74, v75
	s_cbranch_vccz .LBB0_366
	ds_bpermute_b32 v75, v233, v74
	v_max_f32_e32 v74, v74, v74
	s_waitcnt lgkmcnt(0)
	v_max_f32_e32 v75, v75, v75
	v_max_f32_e32 v74, v74, v75
	ds_bpermute_b32 v75, v234, v74
	s_waitcnt lgkmcnt(0)
	v_max3_f32 v74, v193, v74, v75
	v_sub_f32_e32 v75, v193, v74
	v_exp_f32_e32 v96, v75
	v_mov_b32_e32 v193, v74
	v_mul_f32_e32 v191, v191, v96
	v_pk_mul_f32 v[106:107], v[106:107], v[96:97] op_sel_hi:[1,0]
	v_pk_mul_f32 v[104:105], v[104:105], v[96:97] op_sel_hi:[1,0]
	v_pk_mul_f32 v[110:111], v[110:111], v[96:97] op_sel_hi:[1,0]
	v_pk_mul_f32 v[108:109], v[108:109], v[96:97] op_sel_hi:[1,0]
	v_pk_mul_f32 v[114:115], v[114:115], v[96:97] op_sel_hi:[1,0]
	v_pk_mul_f32 v[112:113], v[112:113], v[96:97] op_sel_hi:[1,0]
	v_pk_mul_f32 v[122:123], v[122:123], v[96:97] op_sel_hi:[1,0]
	v_pk_mul_f32 v[120:121], v[120:121], v[96:97] op_sel_hi:[1,0]
	s_branch .LBB0_367

; template <int MODE>
; __device__ __forceinline__ void nsa_compute(int cur, int buf, int t, int hl, u64 mymask, const bf16x8 (&Qf)[2][2], f32x4 (&O)[4][2], float (&m)[2], float (&l)[2],
;                                             const float (&inv)[2], float* impw, char* lds) {
;     ...
;       for (int kk = 0; kk < 2; ++kk)
; #pragma unroll
;         for (int e = 0; e < 4; ++e) {
;           const int off = 32 * s2 + 16 * kk + e;
;           int idx;
;           if (MODE <= 1) { idx = base - 16 * off; idx = idx > 0 ? idx : 0; } else idx = base - off;
;           sv[kk][e] = S[kk][r][e] * (0.125f * LOG2E) + tb[r * TS + idx];
;         }
;       float pv[2][4];
;       if (MODE == 1) {
; #pragma unroll
;         for (int kk = 0; kk < 2; ++kk)
; #pragma unroll
;           for (int e = 0; e < 4; ++e) pv[kk][e] = __builtin_amdgcn_exp2f(sv[kk][e] - m[r]) * inv[r];
; #pragma unroll
;         for (int kk = 0; kk < 2; ++kk) { g1s[kk] += pv[kk][0] + pv[kk][1] + pv[kk][2] + 0.5f * pv[kk][3]; p3s[kk] += 0.5f * pv[kk][3]; }
;       } else {
;         const float mxa = fmaxf(fmaxf(sv[0][0], sv[0][1]), sv[0][2]), mxb = fmaxf(fmaxf(sv[0][3], sv[1][0]), sv[1][1]);
;         float mx = fmaxf(fmaxf(fmaxf(sv[1][2], sv[1][3]), mxa), mxb);
;         if (MODE == 2) mx = selok ? mx : -__builtin_inff();
;         if (__any(mx > m[r] + 8.0f)) {
;           mx = fmaxf(mx, __shfl_xor(mx, 16)); mx = fmaxf(mx, __shfl_xor(mx, 32));
;           const float mn = fmaxf(m[r], mx), al = __builtin_amdgcn_exp2f(m[r] - mn);
;           m[r] = mn; l[r] *= al;
;           if (MODE != 0) {
; #pragma unroll
;             for (int df = 0; df < 4; ++df) O[df][r] *= al;
;           }
;         }
;         const float me = (MODE == 2) ? (selok ? m[r] : __builtin_inff()) : m[r];
;         float ps = 0.f;
; #pragma unroll
;         for (int kk = 0; kk < 2; ++kk)
; #pragma unroll
;           for (int e = 0; e < 4; ++e) { pv[kk][e] = __builtin_amdgcn_exp2f(sv[kk][e] - me); ps += pv[kk][e]; }
;         l[r] += ps;
.LBB0_370:
	v_sub_f32_e32 v115, v123, v120
	v_exp_f32_e32 v115, v115
	v_sub_f32_e32 v117, v118, v120
	v_exp_f32_e32 v117, v117
	v_sub_f32_e32 v118, v122, v120
	v_exp_f32_e32 v118, v118
	v_sub_f32_e32 v116, v116, v120
	v_exp_f32_e32 v116, v116
	v_sub_f32_e32 v119, v119, v120
	v_add_f32_e32 v121, 0, v115
	v_exp_f32_e32 v119, v119
	v_sub_f32_e32 v114, v114, v120
	v_add_f32_e32 v121, v117, v121
	v_exp_f32_e32 v114, v114
	v_add_f32_e32 v121, v118, v121
	v_add_f32_e32 v121, v116, v121
	v_add_f32_e32 v121, v119, v121
	v_sub_f32_e32 v113, v113, v120
	v_add_f32_e32 v122, v114, v121
	v_exp_f32_e32 v121, v113
	v_sub_f32_e32 v112, v112, v120
	v_exp_f32_e32 v120, v112
	v_add_f32_e32 v113, v121, v122
	v_add_f32_e32 v112, v120, v113
	v_add_f32_e32 v190, v190, v112
	v_add_u32_e32 v112, 0xa7c, v136
	ds_read2_b32 v[112:113], v112 offset1:1
	v_add_u32_e32 v222, 0xa74, v136
	ds_read2_b32 v[222:223], v222 offset1:1
	v_add_u32_e32 v230, 0xa3c, v136
	ds_read2_b32 v[230:231], v230 offset1:1
	v_add_u32_e32 v214, 0xa34, v136
	ds_read_b32 v213, v214 offset:4
	ds_read_b32 v214, v214
	s_waitcnt lgkmcnt(4)
	v_fmamk_f32 v113, v100, 0x3e38aa3b, v113
	v_fmac_f32_e32 v112, 0x3e38aa3b, v101
	s_waitcnt lgkmcnt(3)
	v_fmamk_f32 v101, v102, 0x3e38aa3b, v223
	v_fmamk_f32 v100, v103, 0x3e38aa3b, v222
	s_waitcnt lgkmcnt(2)
	v_fmamk_f32 v103, v88, 0x3e38aa3b, v231
	v_fmamk_f32 v102, v89, 0x3e38aa3b, v230
	s_waitcnt lgkmcnt(0)
	v_fmamk_f32 v89, v90, 0x3e38aa3b, v213
	v_fmamk_f32 v88, v91, 0x3e38aa3b, v214
	v_max3_f32 v90, v113, v112, v101
	v_max3_f32 v91, v100, v103, v102
	v_max_f32_e32 v122, v89, v88
	v_max3_f32 v90, v122, v90, v91
	v_add_f32_e32 v91, 0x41000000, v193
	v_cmp_gt_f32_e32 vcc, v90, v91
	s_cbranch_vccz .LBB0_372
	ds_bpermute_b32 v91, v233, v90
	v_max_f32_e32 v90, v90, v90
	s_waitcnt lgkmcnt(0)
	v_max_f32_e32 v91, v91, v91
	v_max_f32_e32 v90, v90, v91
	ds_bpermute_b32 v91, v234, v90
	s_waitcnt lgkmcnt(0)
	v_max3_f32 v90, v193, v90, v91
	v_sub_f32_e32 v91, v193, v90
	v_exp_f32_e32 v122, v91
	v_mov_b32_e32 v193, v90
	v_mul_f32_e32 v191, v191, v122
	v_pk_mul_f32 v[98:99], v[98:99], v[122:123] op_sel_hi:[1,0]
	v_pk_mul_f32 v[96:97], v[96:97], v[122:123] op_sel_hi:[1,0]
	v_pk_mul_f32 v[94:95], v[94:95], v[122:123] op_sel_hi:[1,0]
	v_pk_mul_f32 v[92:93], v[92:93], v[122:123] op_sel_hi:[1,0]
	v_pk_mul_f32 v[110:111], v[110:111], v[122:123] op_sel_hi:[1,0]
	v_pk_mul_f32 v[108:109], v[108:109], v[122:123] op_sel_hi:[1,0]
	v_pk_mul_f32 v[106:107], v[106:107], v[122:123] op_sel_hi:[1,0]
	v_pk_mul_f32 v[104:105], v[104:105], v[122:123] op_sel_hi:[1,0]
	v_mov_b64_e32 v[194:195], v[190:191]
	s_branch .LBB0_373

; template <int MODE>
; __device__ __forceinline__ void nsa_compute(int cur, int buf, int t, int hl, u64 mymask, const bf16x8 (&Qf)[2][2], f32x4 (&O)[4][2], float (&m)[2], float (&l)[2],
;                                             const float (&inv)[2], float* impw, char* lds) {
;     ...
;       for (int kk = 0; kk < 2; ++kk)
; #pragma unroll
;         for (int e = 0; e < 4; ++e) {
;           const int off = 32 * s2 + 16 * kk + e;
;           int idx;
;           if (MODE <= 1) { idx = base - 16 * off; idx = idx > 0 ? idx : 0; } else idx = base - off;
;           sv[kk][e] = S[kk][r][e] * (0.125f * LOG2E) + tb[r * TS + idx];
;         }
;       float pv[2][4];
;       if (MODE == 1) {
; #pragma unroll
;         for (int kk = 0; kk < 2; ++kk)
; #pragma unroll
;           for (int e = 0; e < 4; ++e) pv[kk][e] = __builtin_amdgcn_exp2f(sv[kk][e] - m[r]) * inv[r];
; #pragma unroll
;         for (int kk = 0; kk < 2; ++kk) { g1s[kk] += pv[kk][0] + pv[kk][1] + pv[kk][2] + 0.5f * pv[kk][3]; p3s[kk] += 0.5f * pv[kk][3]; }
;       } else {
;         const float mxa = fmaxf(fmaxf(sv[0][0], sv[0][1]), sv[0][2]), mxb = fmaxf(fmaxf(sv[0][3], sv[1][0]), sv[1][1]);
;         float mx = fmaxf(fmaxf(fmaxf(sv[1][2], sv[1][3]), mxa), mxb);
;         if (MODE == 2) mx = selok ? mx : -__builtin_inff();
;         if (__any(mx > m[r] + 8.0f)) {
;           mx = fmaxf(mx, __shfl_xor(mx, 16)); mx = fmaxf(mx, __shfl_xor(mx, 32));
;           const float mn = fmaxf(m[r], mx), al = __builtin_amdgcn_exp2f(m[r] - mn);
;           m[r] = mn; l[r] *= al;
;           if (MODE != 0) {
; #pragma unroll
;             for (int df = 0; df < 4; ++df) O[df][r] *= al;
;           }
;         }
;         const float me = (MODE == 2) ? (selok ? m[r] : __builtin_inff()) : m[r];
;         float ps = 0.f;
; #pragma unroll
;         for (int kk = 0; kk < 2; ++kk)
; #pragma unroll
;           for (int e = 0; e < 4; ++e) { pv[kk][e] = __builtin_amdgcn_exp2f(sv[kk][e] - me); ps += pv[kk][e]; }
;         l[r] += ps;
.LBB0_382:
	v_sub_f32_e32 v135, v135, v136
	v_exp_f32_e32 v151, v135
	v_sub_f32_e32 v134, v134, v136
	v_exp_f32_e32 v152, v134
	v_sub_f32_e32 v133, v133, v136
	v_exp_f32_e32 v153, v133
	v_sub_f32_e32 v132, v132, v136
	v_exp_f32_e32 v155, v132
	v_sub_f32_e32 v129, v129, v136
	v_add_f32_e32 v135, 0, v151
	v_exp_f32_e32 v156, v129
	v_sub_f32_e32 v128, v128, v136
	v_add_f32_e32 v134, v152, v135
	v_exp_f32_e32 v157, v128
	v_add_f32_e32 v133, v153, v134
	v_add_f32_e32 v132, v155, v133
	v_add_f32_e32 v129, v156, v132
	v_add_f32_e32 v128, v157, v129
	v_sub_f32_e32 v129, v131, v136
	v_exp_f32_e32 v158, v129
	v_sub_f32_e32 v129, v130, v136
	v_exp_f32_e32 v159, v129
	v_add_f32_e32 v128, v158, v128
	v_add_f32_e32 v128, v159, v128
	v_add_f32_e32 v196, v196, v128
	v_add_u32_e32 v134, 0xafc, v154
	ds_read2_b32 v[134:135], v134 offset1:1
	v_add_u32_e32 v144, 0xaf4, v154
	ds_read2_b32 v[144:145], v144 offset1:1
	v_add_u32_e32 v132, 0xabc, v154
	ds_read2_b32 v[132:133], v132 offset1:1
	v_add_u32_e32 v222, 0xab4, v154
	ds_read2_b32 v[222:223], v222 offset1:1
	s_waitcnt lgkmcnt(3)
	v_fmamk_f32 v135, v124, 0x3e38aa3b, v135
	v_fmac_f32_e32 v134, 0x3e38aa3b, v125
	s_waitcnt lgkmcnt(2)
	v_fmamk_f32 v145, v126, 0x3e38aa3b, v145
	v_fmac_f32_e32 v144, 0x3e38aa3b, v127
	s_waitcnt lgkmcnt(1)
	v_fmamk_f32 v133, v116, 0x3e38aa3b, v133
	v_fmac_f32_e32 v132, 0x3e38aa3b, v117
	s_waitcnt lgkmcnt(0)
	v_fmamk_f32 v117, v118, 0x3e38aa3b, v223
	v_fmamk_f32 v116, v119, 0x3e38aa3b, v222
	v_max3_f32 v118, v135, v134, v145
	v_max3_f32 v119, v144, v133, v132
	v_max_f32_e32 v124, v117, v116
	v_max3_f32 v118, v124, v118, v119
	v_add_f32_e32 v119, 0x41000000, v193
	v_cmp_gt_f32_e32 vcc, v118, v119
	s_cbranch_vccz .LBB0_384
	ds_bpermute_b32 v119, v233, v118
	v_max_f32_e32 v118, v118, v118
	s_waitcnt lgkmcnt(0)
	v_max_f32_e32 v119, v119, v119
	v_max_f32_e32 v118, v118, v119
	ds_bpermute_b32 v119, v234, v118
	s_waitcnt lgkmcnt(0)
	v_max3_f32 v118, v193, v118, v119
	v_sub_f32_e32 v119, v193, v118
	v_exp_f32_e32 v140, v119
	v_mov_b32_e32 v193, v118
	v_mul_f32_e32 v197, v197, v140
	v_pk_mul_f32 v[126:127], v[98:99], v[140:141] op_sel_hi:[1,0]
	v_pk_mul_f32 v[124:125], v[96:97], v[140:141] op_sel_hi:[1,0]
	v_pk_mul_f32 v[130:131], v[86:87], v[140:141] op_sel_hi:[1,0]
	v_pk_mul_f32 v[128:129], v[84:85], v[140:141] op_sel_hi:[1,0]
	v_pk_mul_f32 v[138:139], v[78:79], v[140:141] op_sel_hi:[1,0]
	v_pk_mul_f32 v[136:137], v[76:77], v[140:141] op_sel_hi:[1,0]
	v_pk_mul_f32 v[142:143], v[74:75], v[140:141] op_sel_hi:[1,0]
	v_pk_mul_f32 v[140:141], v[72:73], v[140:141] op_sel_hi:[1,0]
	s_branch .LBB0_385

; template <int MODE>
; __device__ __forceinline__ void nsa_compute(int cur, int buf, int t, int hl, u64 mymask, const bf16x8 (&Qf)[2][2], f32x4 (&O)[4][2], float (&m)[2], float (&l)[2],
;                                             const float (&inv)[2], float* impw, char* lds) {
;     ...
;       for (int kk = 0; kk < 2; ++kk)
; #pragma unroll
;         for (int e = 0; e < 4; ++e) {
;           const int off = 32 * s2 + 16 * kk + e;
;           int idx;
;           if (MODE <= 1) { idx = base - 16 * off; idx = idx > 0 ? idx : 0; } else idx = base - off;
;           sv[kk][e] = S[kk][r][e] * (0.125f * LOG2E) + tb[r * TS + idx];
;         }
;       float pv[2][4];
;       if (MODE == 1) {
; #pragma unroll
;         for (int kk = 0; kk < 2; ++kk)
; #pragma unroll
;           for (int e = 0; e < 4; ++e) pv[kk][e] = __builtin_amdgcn_exp2f(sv[kk][e] - m[r]) * inv[r];
; #pragma unroll
;         for (int kk = 0; kk < 2; ++kk) { g1s[kk] += pv[kk][0] + pv[kk][1] + pv[kk][2] + 0.5f * pv[kk][3]; p3s[kk] += 0.5f * pv[kk][3]; }
;       } else {
;         const float mxa = fmaxf(fmaxf(sv[0][0], sv[0][1]), sv[0][2]), mxb = fmaxf(fmaxf(sv[0][3], sv[1][0]), sv[1][1]);
;         float mx = fmaxf(fmaxf(fmaxf(sv[1][2], sv[1][3]), mxa), mxb);
;         if (MODE == 2) mx = selok ? mx : -__builtin_inff();
;         if (__any(mx > m[r] + 8.0f)) {
;           mx = fmaxf(mx, __shfl_xor(mx, 16)); mx = fmaxf(mx, __shfl_xor(mx, 32));
;           const float mn = fmaxf(m[r], mx), al = __builtin_amdgcn_exp2f(m[r] - mn);
;           m[r] = mn; l[r] *= al;
;           if (MODE != 0) {
; #pragma unroll
;             for (int df = 0; df < 4; ++df) O[df][r] *= al;
;           }
;         }
;         const float me = (MODE == 2) ? (selok ? m[r] : __builtin_inff()) : m[r];
;         float ps = 0.f;
; #pragma unroll
;         for (int kk = 0; kk < 2; ++kk)
; #pragma unroll
;           for (int e = 0; e < 4; ++e) { pv[kk][e] = __builtin_amdgcn_exp2f(sv[kk][e] - me); ps += pv[kk][e]; }
;         l[r] += ps;
.LBB0_388:
	v_sub_f32_e32 v147, v160, v152
	v_exp_f32_e32 v147, v147
	v_sub_f32_e32 v149, v150, v152
	v_exp_f32_e32 v149, v149
	v_sub_f32_e32 v150, v159, v152
	v_exp_f32_e32 v150, v150
	v_sub_f32_e32 v148, v148, v152
	v_exp_f32_e32 v148, v148
	v_sub_f32_e32 v151, v151, v152
	v_add_f32_e32 v153, 0, v147
	v_exp_f32_e32 v151, v151
	v_sub_f32_e32 v146, v146, v152
	v_add_f32_e32 v153, v149, v153
	v_exp_f32_e32 v146, v146
	v_add_f32_e32 v153, v150, v153
	v_add_f32_e32 v153, v148, v153
	v_add_f32_e32 v153, v151, v153
	v_sub_f32_e32 v145, v145, v152
	v_add_f32_e32 v159, v146, v153
	v_exp_f32_e32 v153, v145
	v_sub_f32_e32 v144, v144, v152
	v_exp_f32_e32 v152, v144
	v_add_f32_e32 v145, v153, v159
	v_add_f32_e32 v144, v152, v145
	v_add_f32_e32 v196, v196, v144
	v_add_u32_e32 v144, 0xa7c, v154
	ds_read2_b32 v[144:145], v144 offset1:1
	v_add_u32_e32 v222, 0xa74, v154
	ds_read2_b32 v[222:223], v222 offset1:1
	v_add_u32_e32 v230, 0xa3c, v154
	ds_read2_b32 v[230:231], v230 offset1:1
	v_add_u32_e32 v214, 0xa34, v154
	ds_read_b32 v213, v214 offset:4
	ds_read_b32 v214, v214
	s_waitcnt lgkmcnt(4)
	v_fmamk_f32 v145, v140, 0x3e38aa3b, v145
	v_fmac_f32_e32 v144, 0x3e38aa3b, v141
	s_waitcnt lgkmcnt(3)
	v_fmamk_f32 v141, v142, 0x3e38aa3b, v223
	v_fmamk_f32 v140, v143, 0x3e38aa3b, v222
	s_waitcnt lgkmcnt(2)
	v_fmamk_f32 v143, v136, 0x3e38aa3b, v231
	v_fmamk_f32 v142, v137, 0x3e38aa3b, v230
	s_waitcnt lgkmcnt(0)
	v_fmamk_f32 v137, v138, 0x3e38aa3b, v213
	v_fmamk_f32 v136, v139, 0x3e38aa3b, v214
	v_max3_f32 v138, v145, v144, v141
	v_max3_f32 v139, v140, v143, v142
	v_max_f32_e32 v154, v137, v136
	v_max3_f32 v138, v154, v138, v139
	v_add_f32_e32 v139, 0x41000000, v193
	v_cmp_gt_f32_e32 vcc, v138, v139
	s_cbranch_vccz .LBB0_390
	ds_bpermute_b32 v139, v233, v138
	v_max_f32_e32 v138, v138, v138
	s_waitcnt lgkmcnt(0)
	v_max_f32_e32 v139, v139, v139
	v_max_f32_e32 v138, v138, v139
	ds_bpermute_b32 v139, v234, v138
	s_waitcnt lgkmcnt(0)
	v_max3_f32 v138, v193, v138, v139
	v_sub_f32_e32 v139, v193, v138
	v_exp_f32_e32 v154, v139
	v_mov_b32_e32 v193, v138
	v_mul_f32_e32 v197, v197, v154
	v_pk_mul_f32 v[134:135], v[134:135], v[154:155] op_sel_hi:[1,0]
	v_pk_mul_f32 v[132:133], v[132:133], v[154:155] op_sel_hi:[1,0]
	v_pk_mul_f32 v[130:131], v[130:131], v[154:155] op_sel_hi:[1,0]
	v_pk_mul_f32 v[128:129], v[128:129], v[154:155] op_sel_hi:[1,0]
	v_pk_mul_f32 v[126:127], v[126:127], v[154:155] op_sel_hi:[1,0]
	v_pk_mul_f32 v[124:125], v[124:125], v[154:155] op_sel_hi:[1,0]
	v_pk_mul_f32 v[122:123], v[122:123], v[154:155] op_sel_hi:[1,0]
	v_pk_mul_f32 v[120:121], v[120:121], v[154:155] op_sel_hi:[1,0]
	s_branch .LBB0_391

; template <int MODE>
; __device__ __forceinline__ void nsa_compute(int cur, int buf, int t, int hl, u64 mymask, const bf16x8 (&Qf)[2][2], f32x4 (&O)[4][2], float (&m)[2], float (&l)[2],
;                                             const float (&inv)[2], float* impw, char* lds) {
;     ...
;       for (int kk = 0; kk < 2; ++kk)
; #pragma unroll
;         for (int e = 0; e < 4; ++e) {
;           const int off = 32 * s2 + 16 * kk + e;
;           int idx;
;           if (MODE <= 1) { idx = base - 16 * off; idx = idx > 0 ? idx : 0; } else idx = base - off;
;           sv[kk][e] = S[kk][r][e] * (0.125f * LOG2E) + tb[r * TS + idx];
;         }
;       float pv[2][4];
;       if (MODE == 1) {
; #pragma unroll
;         for (int kk = 0; kk < 2; ++kk)
; #pragma unroll
;           for (int e = 0; e < 4; ++e) pv[kk][e] = __builtin_amdgcn_exp2f(sv[kk][e] - m[r]) * inv[r];
; #pragma unroll
;         for (int kk = 0; kk < 2; ++kk) { g1s[kk] += pv[kk][0] + pv[kk][1] + pv[kk][2] + 0.5f * pv[kk][3]; p3s[kk] += 0.5f * pv[kk][3]; }
;       } else {
;         const float mxa = fmaxf(fmaxf(sv[0][0], sv[0][1]), sv[0][2]), mxb = fmaxf(fmaxf(sv[0][3], sv[1][0]), sv[1][1]);
;         float mx = fmaxf(fmaxf(fmaxf(sv[1][2], sv[1][3]), mxa), mxb);
;         if (MODE == 2) mx = selok ? mx : -__builtin_inff();
;         if (__any(mx > m[r] + 8.0f)) {
;           mx = fmaxf(mx, __shfl_xor(mx, 16)); mx = fmaxf(mx, __shfl_xor(mx, 32));
;           const float mn = fmaxf(m[r], mx), al = __builtin_amdgcn_exp2f(m[r] - mn);
;           m[r] = mn; l[r] *= al;
;           if (MODE != 0) {
; #pragma unroll
;             for (int df = 0; df < 4; ++df) O[df][r] *= al;
;           }
;         }
;         const float me = (MODE == 2) ? (selok ? m[r] : __builtin_inff()) : m[r];
;         float ps = 0.f;
; #pragma unroll
;         for (int kk = 0; kk < 2; ++kk)
; #pragma unroll
;           for (int e = 0; e < 4; ++e) { pv[kk][e] = __builtin_amdgcn_exp2f(sv[kk][e] - me); ps += pv[kk][e]; }
;         l[r] += ps;
.LBB0_399:
	v_sub_f32_e32 v135, v135, v168
	v_exp_f32_e32 v202, v135
	v_sub_f32_e32 v134, v134, v168
	v_exp_f32_e32 v203, v134
	v_sub_f32_e32 v133, v133, v168
	v_exp_f32_e32 v204, v133
	v_sub_f32_e32 v132, v132, v168
	v_exp_f32_e32 v205, v132
	v_sub_f32_e32 v129, v129, v168
	v_add_f32_e32 v135, 0, v202
	v_exp_f32_e32 v206, v129
	v_sub_f32_e32 v128, v128, v168
	v_add_f32_e32 v134, v203, v135
	v_exp_f32_e32 v207, v128
	v_add_f32_e32 v133, v204, v134
	v_add_f32_e32 v132, v205, v133
	v_add_f32_e32 v129, v206, v132
	v_add_f32_e32 v128, v207, v129
	v_sub_f32_e32 v129, v131, v168
	v_exp_f32_e32 v236, v129
	v_sub_f32_e32 v129, v130, v168
	v_exp_f32_e32 v237, v129
	v_add_f32_e32 v128, v236, v128
	v_add_f32_e32 v128, v237, v128
	v_add_f32_e32 v190, v190, v128
	v_add_u32_e32 v172, 0xafc, v176
	ds_read2_b32 v[172:173], v172 offset1:1
	v_add_u32_e32 v174, 0xaf4, v176
	ds_read2_b32 v[174:175], v174 offset1:1
	v_add_u32_e32 v222, 0xabc, v176
	ds_read2_b32 v[222:223], v222 offset1:1
	v_add_u32_e32 v230, 0xab4, v176
	ds_read2_b32 v[230:231], v230 offset1:1
	s_waitcnt lgkmcnt(3)
	v_fmamk_f32 v173, v124, 0x3e38aa3b, v173
	v_fmac_f32_e32 v172, 0x3e38aa3b, v125
	s_waitcnt lgkmcnt(2)
	v_fmamk_f32 v175, v126, 0x3e38aa3b, v175
	v_fmac_f32_e32 v174, 0x3e38aa3b, v127
	s_waitcnt lgkmcnt(1)
	v_fmamk_f32 v125, v120, 0x3e38aa3b, v223
	v_fmamk_f32 v124, v121, 0x3e38aa3b, v222
	v_max3_f32 v120, v173, v172, v175
	v_max3_f32 v121, v174, v125, v124
	s_waitcnt lgkmcnt(0)
	v_fmamk_f32 v127, v122, 0x3e38aa3b, v231
	v_fmamk_f32 v126, v123, 0x3e38aa3b, v230
	v_max_f32_e32 v122, v127, v126
	v_max3_f32 v120, v122, v120, v121
	v_add_f32_e32 v121, 0x41000000, v193
	v_cmp_gt_f32_e32 vcc, v120, v121
	s_cbranch_vccz .LBB0_401
	ds_bpermute_b32 v121, v233, v120
	v_max_f32_e32 v120, v120, v120
	s_waitcnt lgkmcnt(0)
	v_max_f32_e32 v121, v121, v121
	v_max_f32_e32 v120, v120, v121
	ds_bpermute_b32 v121, v234, v120
	s_waitcnt lgkmcnt(0)
	v_max3_f32 v238, v193, v120, v121
	v_sub_f32_e32 v120, v193, v238
	v_exp_f32_e32 v168, v120
	v_mov_b32_e32 v193, v238
	v_mul_f32_e32 v191, v191, v168
	v_pk_mul_f32 v[122:123], v[142:143], v[168:169] op_sel_hi:[1,0]
	v_pk_mul_f32 v[120:121], v[140:141], v[168:169] op_sel_hi:[1,0]
	v_pk_mul_f32 v[130:131], v[146:147], v[168:169] op_sel_hi:[1,0]
	v_pk_mul_f32 v[128:129], v[144:145], v[168:169] op_sel_hi:[1,0]
	v_pk_mul_f32 v[134:135], v[150:151], v[168:169] op_sel_hi:[1,0]
	v_pk_mul_f32 v[132:133], v[148:149], v[168:169] op_sel_hi:[1,0]
	v_pk_mul_f32 v[170:171], v[154:155], v[168:169] op_sel_hi:[1,0]
	v_pk_mul_f32 v[168:169], v[152:153], v[168:169] op_sel_hi:[1,0]
	s_branch .LBB0_402

; template <int MODE>
; __device__ __forceinline__ void nsa_compute(int cur, int buf, int t, int hl, u64 mymask, const bf16x8 (&Qf)[2][2], f32x4 (&O)[4][2], float (&m)[2], float (&l)[2],
;                                             const float (&inv)[2], float* impw, char* lds) {
;     ...
;       for (int kk = 0; kk < 2; ++kk)
; #pragma unroll
;         for (int e = 0; e < 4; ++e) {
;           const int off = 32 * s2 + 16 * kk + e;
;           int idx;
;           if (MODE <= 1) { idx = base - 16 * off; idx = idx > 0 ? idx : 0; } else idx = base - off;
;           sv[kk][e] = S[kk][r][e] * (0.125f * LOG2E) + tb[r * TS + idx];
;         }
;       float pv[2][4];
;       if (MODE == 1) {
; #pragma unroll
;         for (int kk = 0; kk < 2; ++kk)
; #pragma unroll
;           for (int e = 0; e < 4; ++e) pv[kk][e] = __builtin_amdgcn_exp2f(sv[kk][e] - m[r]) * inv[r];
; #pragma unroll
;         for (int kk = 0; kk < 2; ++kk) { g1s[kk] += pv[kk][0] + pv[kk][1] + pv[kk][2] + 0.5f * pv[kk][3]; p3s[kk] += 0.5f * pv[kk][3]; }
;       } else {
;         const float mxa = fmaxf(fmaxf(sv[0][0], sv[0][1]), sv[0][2]), mxb = fmaxf(fmaxf(sv[0][3], sv[1][0]), sv[1][1]);
;         float mx = fmaxf(fmaxf(fmaxf(sv[1][2], sv[1][3]), mxa), mxb);
;         if (MODE == 2) mx = selok ? mx : -__builtin_inff();
;         if (__any(mx > m[r] + 8.0f)) {
;           mx = fmaxf(mx, __shfl_xor(mx, 16)); mx = fmaxf(mx, __shfl_xor(mx, 32));
;           const float mn = fmaxf(m[r], mx), al = __builtin_amdgcn_exp2f(m[r] - mn);
;           m[r] = mn; l[r] *= al;
;           if (MODE != 0) {
; #pragma unroll
;             for (int df = 0; df < 4; ++df) O[df][r] *= al;
;           }
;         }
;         const float me = (MODE == 2) ? (selok ? m[r] : __builtin_inff()) : m[r];
;         float ps = 0.f;
; #pragma unroll
;         for (int kk = 0; kk < 2; ++kk)
; #pragma unroll
;           for (int e = 0; e < 4; ++e) { pv[kk][e] = __builtin_amdgcn_exp2f(sv[kk][e] - me); ps += pv[kk][e]; }
;         l[r] += ps;
.LBB0_405:
	v_sub_f32_e32 v201, v241, v206
	v_exp_f32_e32 v201, v201
	v_sub_f32_e32 v203, v204, v206
	v_exp_f32_e32 v203, v203
	v_sub_f32_e32 v204, v240, v206
	v_exp_f32_e32 v204, v204
	v_sub_f32_e32 v202, v202, v206
	v_exp_f32_e32 v202, v202
	v_sub_f32_e32 v205, v205, v206
	v_add_f32_e32 v207, 0, v201
	v_exp_f32_e32 v205, v205
	v_sub_f32_e32 v200, v200, v206
	v_add_f32_e32 v207, v203, v207
	v_exp_f32_e32 v200, v200
	v_add_f32_e32 v207, v204, v207
	v_add_f32_e32 v207, v202, v207
	v_add_f32_e32 v207, v205, v207
	v_sub_f32_e32 v199, v199, v206
	v_add_f32_e32 v208, v200, v207
	v_exp_f32_e32 v207, v199
	v_sub_f32_e32 v198, v198, v206
	v_exp_f32_e32 v206, v198
	v_add_f32_e32 v199, v207, v208
	v_add_f32_e32 v198, v206, v199
	v_add_f32_e32 v190, v190, v198
	v_add_u32_e32 v198, 0xa7c, v176
	ds_read2_b32 v[198:199], v198 offset1:1
	v_add_u32_e32 v222, 0xa74, v176
	ds_read2_b32 v[222:223], v222 offset1:1
	v_add_u32_e32 v230, 0xa3c, v176
	ds_read2_b32 v[230:231], v230 offset1:1
	v_add_u32_e32 v214, 0xa34, v176
	ds_read_b32 v213, v214 offset:4
	ds_read_b32 v214, v214
	s_waitcnt lgkmcnt(4)
	v_fmamk_f32 v199, v172, 0x3e38aa3b, v199
	v_fmac_f32_e32 v198, 0x3e38aa3b, v173
	s_waitcnt lgkmcnt(3)
	v_fmamk_f32 v173, v174, 0x3e38aa3b, v223
	v_fmamk_f32 v172, v175, 0x3e38aa3b, v222
	s_waitcnt lgkmcnt(2)
	v_fmamk_f32 v240, v116, 0x3e38aa3b, v231
	v_fmamk_f32 v174, v117, 0x3e38aa3b, v230
	s_waitcnt lgkmcnt(0)
	v_fmamk_f32 v117, v118, 0x3e38aa3b, v213
	v_fmamk_f32 v116, v119, 0x3e38aa3b, v214
	v_max3_f32 v118, v199, v198, v173
	v_max3_f32 v119, v172, v240, v174
	v_max_f32_e32 v175, v117, v116
	v_max3_f32 v118, v175, v118, v119
	v_add_f32_e32 v119, 0x41000000, v193
	v_cmp_gt_f32_e32 vcc, v118, v119
	s_cbranch_vccz .LBB0_407
	ds_bpermute_b32 v119, v233, v118
	v_max_f32_e32 v118, v118, v118
	s_waitcnt lgkmcnt(0)
	v_max_f32_e32 v119, v119, v119
	v_max_f32_e32 v118, v118, v119
	ds_bpermute_b32 v119, v234, v118
	s_waitcnt lgkmcnt(0)
	v_max3_f32 v118, v193, v118, v119
	v_sub_f32_e32 v119, v193, v118
	v_exp_f32_e32 v176, v119
	v_mov_b32_e32 v193, v118
	v_mul_f32_e32 v191, v191, v176
	v_pk_mul_f32 v[126:127], v[126:127], v[176:177] op_sel_hi:[1,0]
	v_pk_mul_f32 v[124:125], v[124:125], v[176:177] op_sel_hi:[1,0]
	v_pk_mul_f32 v[130:131], v[130:131], v[176:177] op_sel_hi:[1,0]
	v_pk_mul_f32 v[128:129], v[128:129], v[176:177] op_sel_hi:[1,0]
	v_pk_mul_f32 v[134:135], v[134:135], v[176:177] op_sel_hi:[1,0]
	v_pk_mul_f32 v[132:133], v[132:133], v[176:177] op_sel_hi:[1,0]
	v_pk_mul_f32 v[170:171], v[170:171], v[176:177] op_sel_hi:[1,0]
	v_pk_mul_f32 v[168:169], v[168:169], v[176:177] op_sel_hi:[1,0]
	s_branch .LBB0_408

; template <int MODE>
; __device__ __forceinline__ void nsa_compute(int cur, int buf, int t, int hl, u64 mymask, const bf16x8 (&Qf)[2][2], f32x4 (&O)[4][2], float (&m)[2], float (&l)[2],
;                                             const float (&inv)[2], float* impw, char* lds) {
;     ...
;       for (int kk = 0; kk < 2; ++kk)
; #pragma unroll
;         for (int e = 0; e < 4; ++e) {
;           const int off = 32 * s2 + 16 * kk + e;
;           int idx;
;           if (MODE <= 1) { idx = base - 16 * off; idx = idx > 0 ? idx : 0; } else idx = base - off;
;           sv[kk][e] = S[kk][r][e] * (0.125f * LOG2E) + tb[r * TS + idx];
;         }
;       float pv[2][4];
;       if (MODE == 1) {
; #pragma unroll
;         for (int kk = 0; kk < 2; ++kk)
; #pragma unroll
;           for (int e = 0; e < 4; ++e) pv[kk][e] = __builtin_amdgcn_exp2f(sv[kk][e] - m[r]) * inv[r];
; #pragma unroll
;         for (int kk = 0; kk < 2; ++kk) { g1s[kk] += pv[kk][0] + pv[kk][1] + pv[kk][2] + 0.5f * pv[kk][3]; p3s[kk] += 0.5f * pv[kk][3]; }
;       } else {
;         const float mxa = fmaxf(fmaxf(sv[0][0], sv[0][1]), sv[0][2]), mxb = fmaxf(fmaxf(sv[0][3], sv[1][0]), sv[1][1]);
;         float mx = fmaxf(fmaxf(fmaxf(sv[1][2], sv[1][3]), mxa), mxb);
;         if (MODE == 2) mx = selok ? mx : -__builtin_inff();
;         if (__any(mx > m[r] + 8.0f)) {
;           mx = fmaxf(mx, __shfl_xor(mx, 16)); mx = fmaxf(mx, __shfl_xor(mx, 32));
;           const float mn = fmaxf(m[r], mx), al = __builtin_amdgcn_exp2f(m[r] - mn);
;           m[r] = mn; l[r] *= al;
;           if (MODE != 0) {
; #pragma unroll
;             for (int df = 0; df < 4; ++df) O[df][r] *= al;
;           }
;         }
;         const float me = (MODE == 2) ? (selok ? m[r] : __builtin_inff()) : m[r];
;         float ps = 0.f;
; #pragma unroll
;         for (int kk = 0; kk < 2; ++kk)
; #pragma unroll
;           for (int e = 0; e < 4; ++e) { pv[kk][e] = __builtin_amdgcn_exp2f(sv[kk][e] - me); ps += pv[kk][e]; }
;         l[r] += ps;
.LBB0_439:
	v_cndmask_b32_e64 v98, v88, v228, s[36:37]
	v_sub_f32_e32 v85, v87, v98
	v_exp_f32_e32 v85, v85
	v_sub_f32_e32 v86, v86, v98
	v_exp_f32_e32 v86, v86
	v_sub_f32_e32 v83, v83, v98
	v_add_f32_e32 v87, 0, v85
	v_sub_f32_e32 v82, v82, v98
	v_add_f32_e32 v88, v86, v87
	v_exp_f32_e32 v87, v83
	v_sub_f32_e32 v81, v81, v98
	v_exp_f32_e32 v89, v81
	v_sub_f32_e32 v80, v80, v98
	v_add_f32_e32 v83, v87, v88
	v_exp_f32_e32 v88, v82
	v_exp_f32_e32 v96, v80
	v_add_f32_e32 v82, v88, v83
	v_add_f32_e32 v81, v89, v82
	v_add_f32_e32 v80, v96, v81
	v_sub_f32_e32 v81, v97, v98
	v_exp_f32_e32 v97, v81
	v_sub_f32_e32 v81, v84, v98
	v_exp_f32_e32 v84, v81
	v_add_f32_e32 v80, v97, v80
	v_add_f32_e32 v80, v84, v80
	v_add_f32_e32 v190, v190, v80
	v_add_u32_e32 v80, 0xc5fc, v90
	ds_read2_b32 v[80:81], v80 offset1:1
	v_add_u32_e32 v82, 0xc5f4, v90
	ds_read2_b32 v[82:83], v82 offset1:1
	v_add_u32_e32 v222, 0xc5bc, v90
	ds_read2_b32 v[222:223], v222 offset1:1
	v_add_u32_e32 v230, 0xc5b4, v90
	ds_read2_b32 v[230:231], v230 offset1:1
	s_waitcnt lgkmcnt(3)
	v_fmamk_f32 v81, v76, 0x3e38aa3b, v81
	v_fmac_f32_e32 v80, 0x3e38aa3b, v77
	s_waitcnt lgkmcnt(2)
	v_fmamk_f32 v78, v78, 0x3e38aa3b, v83
	v_fmac_f32_e32 v82, 0x3e38aa3b, v79
	s_waitcnt lgkmcnt(1)
	v_fmamk_f32 v77, v72, 0x3e38aa3b, v223
	v_fmamk_f32 v76, v73, 0x3e38aa3b, v222
	s_waitcnt lgkmcnt(0)
	v_fmamk_f32 v73, v74, 0x3e38aa3b, v231
	v_fmamk_f32 v72, v75, 0x3e38aa3b, v230
	v_max3_f32 v74, v81, v80, v78
	v_max3_f32 v75, v82, v77, v76
	v_max_f32_e32 v79, v73, v72
	v_max3_f32 v74, v79, v74, v75
	v_cndmask_b32_e64 v74, v74, v225, s[36:37]
	v_add_f32_e32 v75, 0x41000000, v189
	v_cmp_gt_f32_e32 vcc, v74, v75
	s_cbranch_vccz .LBB0_441
	ds_bpermute_b32 v75, v233, v74
	v_max_f32_e32 v74, v74, v74
	s_waitcnt lgkmcnt(0)
	v_max_f32_e32 v75, v75, v75
	v_max_f32_e32 v74, v74, v75
	ds_bpermute_b32 v75, v234, v74
	s_waitcnt lgkmcnt(0)
	v_max3_f32 v74, v189, v74, v75
	v_sub_f32_e32 v75, v189, v74
	v_exp_f32_e32 v98, v75
	v_mov_b32_e32 v189, v74
	v_mul_f32_e32 v191, v191, v98
	v_pk_mul_f32 v[22:23], v[22:23], v[98:99] op_sel_hi:[1,0]
	v_pk_mul_f32 v[20:21], v[20:21], v[98:99] op_sel_hi:[1,0]
	v_pk_mul_f32 v[30:31], v[30:31], v[98:99] op_sel_hi:[1,0]
	v_pk_mul_f32 v[28:29], v[28:29], v[98:99] op_sel_hi:[1,0]
	v_pk_mul_f32 v[38:39], v[38:39], v[98:99] op_sel_hi:[1,0]
	v_pk_mul_f32 v[36:37], v[36:37], v[98:99] op_sel_hi:[1,0]
	v_pk_mul_f32 v[46:47], v[46:47], v[98:99] op_sel_hi:[1,0]
	v_pk_mul_f32 v[44:45], v[44:45], v[98:99] op_sel_hi:[1,0]
	s_branch .LBB0_442

; template <int MODE>
; __device__ __forceinline__ void nsa_compute(int cur, int buf, int t, int hl, u64 mymask, const bf16x8 (&Qf)[2][2], f32x4 (&O)[4][2], float (&m)[2], float (&l)[2],
;                                             const float (&inv)[2], float* impw, char* lds) {
;     ...
;       for (int kk = 0; kk < 2; ++kk)
; #pragma unroll
;         for (int e = 0; e < 4; ++e) {
;           const int off = 32 * s2 + 16 * kk + e;
;           int idx;
;           if (MODE <= 1) { idx = base - 16 * off; idx = idx > 0 ? idx : 0; } else idx = base - off;
;           sv[kk][e] = S[kk][r][e] * (0.125f * LOG2E) + tb[r * TS + idx];
;         }
;       float pv[2][4];
;       if (MODE == 1) {
; #pragma unroll
;         for (int kk = 0; kk < 2; ++kk)
; #pragma unroll
;           for (int e = 0; e < 4; ++e) pv[kk][e] = __builtin_amdgcn_exp2f(sv[kk][e] - m[r]) * inv[r];
; #pragma unroll
;         for (int kk = 0; kk < 2; ++kk) { g1s[kk] += pv[kk][0] + pv[kk][1] + pv[kk][2] + 0.5f * pv[kk][3]; p3s[kk] += 0.5f * pv[kk][3]; }
;       } else {
;         const float mxa = fmaxf(fmaxf(sv[0][0], sv[0][1]), sv[0][2]), mxb = fmaxf(fmaxf(sv[0][3], sv[1][0]), sv[1][1]);
;         float mx = fmaxf(fmaxf(fmaxf(sv[1][2], sv[1][3]), mxa), mxb);
;         if (MODE == 2) mx = selok ? mx : -__builtin_inff();
;         if (__any(mx > m[r] + 8.0f)) {
;           mx = fmaxf(mx, __shfl_xor(mx, 16)); mx = fmaxf(mx, __shfl_xor(mx, 32));
;           const float mn = fmaxf(m[r], mx), al = __builtin_amdgcn_exp2f(m[r] - mn);
;           m[r] = mn; l[r] *= al;
;           if (MODE != 0) {
; #pragma unroll
;             for (int df = 0; df < 4; ++df) O[df][r] *= al;
;           }
;         }
;         const float me = (MODE == 2) ? (selok ? m[r] : __builtin_inff()) : m[r];
;         float ps = 0.f;
; #pragma unroll
;         for (int kk = 0; kk < 2; ++kk)
; #pragma unroll
;           for (int e = 0; e < 4; ++e) { pv[kk][e] = __builtin_amdgcn_exp2f(sv[kk][e] - me); ps += pv[kk][e]; }
;         l[r] += ps;
.LBB0_445:
	v_cndmask_b32_e64 v93, v88, v228, s[36:37]
	v_sub_f32_e32 v47, v91, v93
	v_exp_f32_e32 v47, v47
	v_sub_f32_e32 v84, v84, v93
	v_exp_f32_e32 v84, v84
	v_sub_f32_e32 v85, v85, v93
	v_exp_f32_e32 v85, v85
	v_sub_f32_e32 v46, v46, v93
	v_exp_f32_e32 v46, v46
	v_add_f32_e32 v87, 0, v47
	v_add_f32_e32 v87, v84, v87
	v_add_f32_e32 v87, v85, v87
	v_sub_f32_e32 v45, v45, v93
	v_add_f32_e32 v88, v46, v87
	v_exp_f32_e32 v87, v45
	v_sub_f32_e32 v44, v44, v93
	v_add_f32_e32 v45, v87, v88
	v_exp_f32_e32 v88, v44
	s_nop 0
	v_add_f32_e32 v44, v88, v45
	v_sub_f32_e32 v45, v92, v93
	v_exp_f32_e32 v89, v45
	v_sub_f32_e32 v45, v86, v93
	v_exp_f32_e32 v86, v45
	v_add_f32_e32 v44, v89, v44
	v_add_f32_e32 v44, v86, v44
	v_add_f32_e32 v190, v190, v44
	v_add_u32_e32 v44, 0xc57c, v90
	ds_read2_b32 v[44:45], v44 offset1:1
	v_add_u32_e32 v222, 0xc574, v90
	ds_read2_b32 v[222:223], v222 offset1:1
	v_add_u32_e32 v230, 0xc53c, v90
	ds_read2_b32 v[230:231], v230 offset1:1
	v_add_u32_e32 v214, 0xc534, v90
	ds_read_b32 v213, v214 offset:4
	ds_read_b32 v214, v214
	s_waitcnt lgkmcnt(4)
	v_fmamk_f32 v45, v40, 0x3e38aa3b, v45
	v_fmac_f32_e32 v44, 0x3e38aa3b, v41
	s_waitcnt lgkmcnt(3)
	v_fmamk_f32 v41, v42, 0x3e38aa3b, v223
	v_fmamk_f32 v40, v43, 0x3e38aa3b, v222
	s_waitcnt lgkmcnt(2)
	v_fmamk_f32 v43, v36, 0x3e38aa3b, v231
	v_fmamk_f32 v42, v37, 0x3e38aa3b, v230
	s_waitcnt lgkmcnt(0)
	v_fmamk_f32 v90, v38, 0x3e38aa3b, v213
	v_fmamk_f32 v36, v39, 0x3e38aa3b, v214
	v_max3_f32 v37, v45, v44, v41
	v_max3_f32 v38, v40, v43, v42
	v_max_f32_e32 v39, v90, v36
	v_max3_f32 v37, v39, v37, v38
	v_cndmask_b32_e64 v37, v37, v225, s[36:37]
	v_add_f32_e32 v38, 0x41000000, v189
	v_cmp_gt_f32_e32 vcc, v37, v38
	s_cbranch_vccz .LBB0_447
	ds_bpermute_b32 v38, v233, v37
	v_max_f32_e32 v37, v37, v37
	s_waitcnt lgkmcnt(0)
	v_max_f32_e32 v38, v38, v38
	v_max_f32_e32 v37, v37, v38
	ds_bpermute_b32 v38, v234, v37
	s_waitcnt lgkmcnt(0)
	v_max3_f32 v37, v189, v37, v38
	v_sub_f32_e32 v38, v189, v37
	v_exp_f32_e32 v38, v38
	v_mov_b32_e32 v189, v37
	v_mul_f32_e32 v191, v191, v38
	v_pk_mul_f32 v[82:83], v[82:83], v[38:39] op_sel_hi:[1,0]
	v_pk_mul_f32 v[80:81], v[80:81], v[38:39] op_sel_hi:[1,0]
	v_pk_mul_f32 v[78:79], v[78:79], v[38:39] op_sel_hi:[1,0]
	v_pk_mul_f32 v[76:77], v[76:77], v[38:39] op_sel_hi:[1,0]
	v_pk_mul_f32 v[34:35], v[34:35], v[38:39] op_sel_hi:[1,0]
	v_pk_mul_f32 v[32:33], v[32:33], v[38:39] op_sel_hi:[1,0]
	v_pk_mul_f32 v[30:31], v[30:31], v[38:39] op_sel_hi:[1,0]
	v_pk_mul_f32 v[28:29], v[28:29], v[38:39] op_sel_hi:[1,0]
	v_mov_b64_e32 v[144:145], v[190:191]
	s_branch .LBB0_448

; template <int MODE>
; __device__ __forceinline__ void nsa_compute(int cur, int buf, int t, int hl, u64 mymask, const bf16x8 (&Qf)[2][2], f32x4 (&O)[4][2], float (&m)[2], float (&l)[2],
;                                             const float (&inv)[2], float* impw, char* lds) {
;     ...
;       for (int kk = 0; kk < 2; ++kk)
; #pragma unroll
;         for (int e = 0; e < 4; ++e) {
;           const int off = 32 * s2 + 16 * kk + e;
;           int idx;
;           if (MODE <= 1) { idx = base - 16 * off; idx = idx > 0 ? idx : 0; } else idx = base - off;
;           sv[kk][e] = S[kk][r][e] * (0.125f * LOG2E) + tb[r * TS + idx];
;         }
;       float pv[2][4];
;       if (MODE == 1) {
; #pragma unroll
;         for (int kk = 0; kk < 2; ++kk)
; #pragma unroll
;           for (int e = 0; e < 4; ++e) pv[kk][e] = __builtin_amdgcn_exp2f(sv[kk][e] - m[r]) * inv[r];
; #pragma unroll
;         for (int kk = 0; kk < 2; ++kk) { g1s[kk] += pv[kk][0] + pv[kk][1] + pv[kk][2] + 0.5f * pv[kk][3]; p3s[kk] += 0.5f * pv[kk][3]; }
;       } else {
;         const float mxa = fmaxf(fmaxf(sv[0][0], sv[0][1]), sv[0][2]), mxb = fmaxf(fmaxf(sv[0][3], sv[1][0]), sv[1][1]);
;         float mx = fmaxf(fmaxf(fmaxf(sv[1][2], sv[1][3]), mxa), mxb);
;         if (MODE == 2) mx = selok ? mx : -__builtin_inff();
;         if (__any(mx > m[r] + 8.0f)) {
;           mx = fmaxf(mx, __shfl_xor(mx, 16)); mx = fmaxf(mx, __shfl_xor(mx, 32));
;           const float mn = fmaxf(m[r], mx), al = __builtin_amdgcn_exp2f(m[r] - mn);
;           m[r] = mn; l[r] *= al;
;           if (MODE != 0) {
; #pragma unroll
;             for (int df = 0; df < 4; ++df) O[df][r] *= al;
;           }
;         }
;         const float me = (MODE == 2) ? (selok ? m[r] : __builtin_inff()) : m[r];
;         float ps = 0.f;
; #pragma unroll
;         for (int kk = 0; kk < 2; ++kk)
; #pragma unroll
;           for (int e = 0; e < 4; ++e) { pv[kk][e] = __builtin_amdgcn_exp2f(sv[kk][e] - me); ps += pv[kk][e]; }
;         l[r] += ps;
.LBB0_456:
	v_cndmask_b32_e64 v104, v104, v228, s[36:37]
	v_sub_f32_e32 v47, v47, v104
	v_exp_f32_e32 v119, v47
	v_sub_f32_e32 v46, v46, v104
	v_exp_f32_e32 v120, v46
	v_sub_f32_e32 v43, v43, v104
	v_exp_f32_e32 v121, v43
	v_sub_f32_e32 v42, v42, v104
	v_exp_f32_e32 v123, v42
	v_sub_f32_e32 v41, v41, v104
	v_add_f32_e32 v47, 0, v119
	v_exp_f32_e32 v124, v41
	v_sub_f32_e32 v40, v40, v104
	v_add_f32_e32 v46, v120, v47
	v_exp_f32_e32 v125, v40
	v_add_f32_e32 v43, v121, v46
	v_add_f32_e32 v42, v123, v43
	v_add_f32_e32 v41, v124, v42
	v_add_f32_e32 v40, v125, v41
	v_sub_f32_e32 v41, v45, v104
	v_exp_f32_e32 v126, v41
	v_sub_f32_e32 v41, v44, v104
	v_exp_f32_e32 v127, v41
	v_add_f32_e32 v40, v126, v40
	v_add_f32_e32 v40, v127, v40
	v_add_f32_e32 v146, v146, v40
	v_add_u32_e32 v46, 0xc5fc, v122
	ds_read2_b32 v[46:47], v46 offset1:1
	v_add_u32_e32 v112, 0xc5f4, v122
	ds_read2_b32 v[112:113], v112 offset1:1
	v_add_u32_e32 v44, 0xc5bc, v122
	ds_read2_b32 v[44:45], v44 offset1:1
	v_add_u32_e32 v222, 0xc5b4, v122
	ds_read2_b32 v[222:223], v222 offset1:1
	s_waitcnt lgkmcnt(3)
	v_fmamk_f32 v47, v36, 0x3e38aa3b, v47
	v_fmac_f32_e32 v46, 0x3e38aa3b, v37
	s_waitcnt lgkmcnt(2)
	v_fmamk_f32 v113, v38, 0x3e38aa3b, v113
	v_fmac_f32_e32 v112, 0x3e38aa3b, v39
	s_waitcnt lgkmcnt(1)
	v_fmamk_f32 v45, v28, 0x3e38aa3b, v45
	v_fmac_f32_e32 v44, 0x3e38aa3b, v29
	s_waitcnt lgkmcnt(0)
	v_fmamk_f32 v29, v30, 0x3e38aa3b, v223
	v_fmamk_f32 v28, v31, 0x3e38aa3b, v222
	v_max3_f32 v30, v47, v46, v113
	v_max3_f32 v31, v112, v45, v44
	v_max_f32_e32 v36, v29, v28
	v_max3_f32 v30, v36, v30, v31
	v_cndmask_b32_e64 v30, v30, v225, s[36:37]
	v_add_f32_e32 v31, 0x41000000, v189
	v_cmp_gt_f32_e32 vcc, v30, v31
	s_cbranch_vccz .LBB0_458
	ds_bpermute_b32 v31, v233, v30
	v_max_f32_e32 v30, v30, v30
	s_waitcnt lgkmcnt(0)
	v_max_f32_e32 v31, v31, v31
	v_max_f32_e32 v30, v30, v31
	ds_bpermute_b32 v31, v234, v30
	s_waitcnt lgkmcnt(0)
	v_max3_f32 v30, v189, v30, v31
	v_sub_f32_e32 v31, v189, v30
	v_exp_f32_e32 v108, v31
	v_mov_b32_e32 v189, v30
	v_mul_f32_e32 v147, v147, v108
	v_pk_mul_f32 v[38:39], v[98:99], v[108:109] op_sel_hi:[1,0]
	v_pk_mul_f32 v[36:37], v[96:97], v[108:109] op_sel_hi:[1,0]
	v_pk_mul_f32 v[42:43], v[86:87], v[108:109] op_sel_hi:[1,0]
	v_pk_mul_f32 v[40:41], v[84:85], v[108:109] op_sel_hi:[1,0]
	v_pk_mul_f32 v[106:107], v[78:79], v[108:109] op_sel_hi:[1,0]
	v_pk_mul_f32 v[104:105], v[76:77], v[108:109] op_sel_hi:[1,0]
	v_pk_mul_f32 v[110:111], v[74:75], v[108:109] op_sel_hi:[1,0]
	v_pk_mul_f32 v[108:109], v[72:73], v[108:109] op_sel_hi:[1,0]
	s_branch .LBB0_459

; template <int MODE>
; __device__ __forceinline__ void nsa_compute(int cur, int buf, int t, int hl, u64 mymask, const bf16x8 (&Qf)[2][2], f32x4 (&O)[4][2], float (&m)[2], float (&l)[2],
;                                             const float (&inv)[2], float* impw, char* lds) {
;     ...
;       for (int kk = 0; kk < 2; ++kk)
; #pragma unroll
;         for (int e = 0; e < 4; ++e) {
;           const int off = 32 * s2 + 16 * kk + e;
;           int idx;
;           if (MODE <= 1) { idx = base - 16 * off; idx = idx > 0 ? idx : 0; } else idx = base - off;
;           sv[kk][e] = S[kk][r][e] * (0.125f * LOG2E) + tb[r * TS + idx];
;         }
;       float pv[2][4];
;       if (MODE == 1) {
; #pragma unroll
;         for (int kk = 0; kk < 2; ++kk)
; #pragma unroll
;           for (int e = 0; e < 4; ++e) pv[kk][e] = __builtin_amdgcn_exp2f(sv[kk][e] - m[r]) * inv[r];
; #pragma unroll
;         for (int kk = 0; kk < 2; ++kk) { g1s[kk] += pv[kk][0] + pv[kk][1] + pv[kk][2] + 0.5f * pv[kk][3]; p3s[kk] += 0.5f * pv[kk][3]; }
;       } else {
;         const float mxa = fmaxf(fmaxf(sv[0][0], sv[0][1]), sv[0][2]), mxb = fmaxf(fmaxf(sv[0][3], sv[1][0]), sv[1][1]);
;         float mx = fmaxf(fmaxf(fmaxf(sv[1][2], sv[1][3]), mxa), mxb);
;         if (MODE == 2) mx = selok ? mx : -__builtin_inff();
;         if (__any(mx > m[r] + 8.0f)) {
;           mx = fmaxf(mx, __shfl_xor(mx, 16)); mx = fmaxf(mx, __shfl_xor(mx, 32));
;           const float mn = fmaxf(m[r], mx), al = __builtin_amdgcn_exp2f(m[r] - mn);
;           m[r] = mn; l[r] *= al;
;           if (MODE != 0) {
; #pragma unroll
;             for (int df = 0; df < 4; ++df) O[df][r] *= al;
;           }
;         }
;         const float me = (MODE == 2) ? (selok ? m[r] : __builtin_inff()) : m[r];
;         float ps = 0.f;
; #pragma unroll
;         for (int kk = 0; kk < 2; ++kk)
; #pragma unroll
;           for (int e = 0; e < 4; ++e) { pv[kk][e] = __builtin_amdgcn_exp2f(sv[kk][e] - me); ps += pv[kk][e]; }
;         l[r] += ps;
.LBB0_462:
	v_cndmask_b32_e64 v129, v120, v228, s[36:37]
	v_sub_f32_e32 v115, v127, v129
	v_exp_f32_e32 v115, v115
	v_sub_f32_e32 v116, v116, v129
	v_exp_f32_e32 v116, v116
	v_sub_f32_e32 v117, v117, v129
	v_exp_f32_e32 v117, v117
	v_sub_f32_e32 v114, v114, v129
	v_exp_f32_e32 v114, v114
	v_add_f32_e32 v119, 0, v115
	v_add_f32_e32 v119, v116, v119
	v_add_f32_e32 v119, v117, v119
	v_sub_f32_e32 v113, v113, v129
	v_add_f32_e32 v120, v114, v119
	v_exp_f32_e32 v119, v113
	v_sub_f32_e32 v112, v112, v129
	v_add_f32_e32 v113, v119, v120
	v_exp_f32_e32 v120, v112
	s_nop 0
	v_add_f32_e32 v112, v120, v113
	v_sub_f32_e32 v113, v128, v129
	v_exp_f32_e32 v121, v113
	v_sub_f32_e32 v113, v118, v129
	v_exp_f32_e32 v118, v113
	v_add_f32_e32 v112, v121, v112
	v_add_f32_e32 v112, v118, v112
	v_add_f32_e32 v146, v146, v112
	v_add_u32_e32 v112, 0xc57c, v122
	ds_read2_b32 v[112:113], v112 offset1:1
	v_add_u32_e32 v222, 0xc574, v122
	ds_read2_b32 v[222:223], v222 offset1:1
	v_add_u32_e32 v230, 0xc53c, v122
	ds_read2_b32 v[230:231], v230 offset1:1
	v_add_u32_e32 v214, 0xc534, v122
	ds_read_b32 v213, v214 offset:4
	ds_read_b32 v214, v214
	s_waitcnt lgkmcnt(4)
	v_fmamk_f32 v113, v108, 0x3e38aa3b, v113
	v_fmac_f32_e32 v112, 0x3e38aa3b, v109
	s_waitcnt lgkmcnt(3)
	v_fmamk_f32 v109, v110, 0x3e38aa3b, v223
	v_fmamk_f32 v108, v111, 0x3e38aa3b, v222
	s_waitcnt lgkmcnt(2)
	v_fmamk_f32 v111, v104, 0x3e38aa3b, v231
	v_fmamk_f32 v110, v105, 0x3e38aa3b, v230
	s_waitcnt lgkmcnt(0)
	v_fmamk_f32 v105, v106, 0x3e38aa3b, v213
	v_fmamk_f32 v104, v107, 0x3e38aa3b, v214
	v_max3_f32 v106, v113, v112, v109
	v_max3_f32 v107, v108, v111, v110
	v_max_f32_e32 v122, v105, v104
	v_max3_f32 v106, v122, v106, v107
	v_cndmask_b32_e64 v106, v106, v225, s[36:37]
	v_add_f32_e32 v107, 0x41000000, v189
	v_cmp_gt_f32_e32 vcc, v106, v107
	s_cbranch_vccz .LBB0_464
	ds_bpermute_b32 v107, v233, v106
	v_max_f32_e32 v106, v106, v106
	s_waitcnt lgkmcnt(0)
	v_max_f32_e32 v107, v107, v107
	v_max_f32_e32 v106, v106, v107
	ds_bpermute_b32 v107, v234, v106
	s_waitcnt lgkmcnt(0)
	v_max3_f32 v106, v189, v106, v107
	v_sub_f32_e32 v107, v189, v106
	v_exp_f32_e32 v122, v107
	v_mov_b32_e32 v189, v106
	v_mul_f32_e32 v147, v147, v122
	v_pk_mul_f32 v[46:47], v[46:47], v[122:123] op_sel_hi:[1,0]
	v_pk_mul_f32 v[44:45], v[44:45], v[122:123] op_sel_hi:[1,0]
	v_pk_mul_f32 v[42:43], v[42:43], v[122:123] op_sel_hi:[1,0]
	v_pk_mul_f32 v[40:41], v[40:41], v[122:123] op_sel_hi:[1,0]
	v_pk_mul_f32 v[38:39], v[38:39], v[122:123] op_sel_hi:[1,0]
	v_pk_mul_f32 v[36:37], v[36:37], v[122:123] op_sel_hi:[1,0]
	v_pk_mul_f32 v[34:35], v[34:35], v[122:123] op_sel_hi:[1,0]
	v_pk_mul_f32 v[32:33], v[32:33], v[122:123] op_sel_hi:[1,0]
	s_branch .LBB0_465

; template <int MODE>
; __device__ __forceinline__ void nsa_compute(int cur, int buf, int t, int hl, u64 mymask, const bf16x8 (&Qf)[2][2], f32x4 (&O)[4][2], float (&m)[2], float (&l)[2],
;                                             const float (&inv)[2], float* impw, char* lds) {
;     ...
;       for (int kk = 0; kk < 2; ++kk)
; #pragma unroll
;         for (int e = 0; e < 4; ++e) {
;           const int off = 32 * s2 + 16 * kk + e;
;           int idx;
;           if (MODE <= 1) { idx = base - 16 * off; idx = idx > 0 ? idx : 0; } else idx = base - off;
;           sv[kk][e] = S[kk][r][e] * (0.125f * LOG2E) + tb[r * TS + idx];
;         }
;       float pv[2][4];
;       if (MODE == 1) {
; #pragma unroll
;         for (int kk = 0; kk < 2; ++kk)
; #pragma unroll
;           for (int e = 0; e < 4; ++e) pv[kk][e] = __builtin_amdgcn_exp2f(sv[kk][e] - m[r]) * inv[r];
; #pragma unroll
;         for (int kk = 0; kk < 2; ++kk) { g1s[kk] += pv[kk][0] + pv[kk][1] + pv[kk][2] + 0.5f * pv[kk][3]; p3s[kk] += 0.5f * pv[kk][3]; }
;       } else {
;         const float mxa = fmaxf(fmaxf(sv[0][0], sv[0][1]), sv[0][2]), mxb = fmaxf(fmaxf(sv[0][3], sv[1][0]), sv[1][1]);
;         float mx = fmaxf(fmaxf(fmaxf(sv[1][2], sv[1][3]), mxa), mxb);
;         if (MODE == 2) mx = selok ? mx : -__builtin_inff();
;         if (__any(mx > m[r] + 8.0f)) {
;           mx = fmaxf(mx, __shfl_xor(mx, 16)); mx = fmaxf(mx, __shfl_xor(mx, 32));
;           const float mn = fmaxf(m[r], mx), al = __builtin_amdgcn_exp2f(m[r] - mn);
;           m[r] = mn; l[r] *= al;
;           if (MODE != 0) {
; #pragma unroll
;             for (int df = 0; df < 4; ++df) O[df][r] *= al;
;           }
;         }
;         const float me = (MODE == 2) ? (selok ? m[r] : __builtin_inff()) : m[r];
;         float ps = 0.f;
; #pragma unroll
;         for (int kk = 0; kk < 2; ++kk)
; #pragma unroll
;           for (int e = 0; e < 4; ++e) { pv[kk][e] = __builtin_amdgcn_exp2f(sv[kk][e] - me); ps += pv[kk][e]; }
;         l[r] += ps;
.LBB0_473:
	v_cndmask_b32_e64 v136, v136, v228, s[36:37]
	v_sub_f32_e32 v47, v47, v136
	v_exp_f32_e32 v152, v47
	v_sub_f32_e32 v46, v46, v136
	v_exp_f32_e32 v153, v46
	v_sub_f32_e32 v39, v39, v136
	v_exp_f32_e32 v154, v39
	v_sub_f32_e32 v38, v38, v136
	v_exp_f32_e32 v155, v38
	v_sub_f32_e32 v37, v37, v136
	v_add_f32_e32 v47, 0, v152
	v_exp_f32_e32 v156, v37
	v_sub_f32_e32 v36, v36, v136
	v_add_f32_e32 v46, v153, v47
	v_exp_f32_e32 v157, v36
	v_add_f32_e32 v39, v154, v46
	v_add_f32_e32 v38, v155, v39
	v_add_f32_e32 v37, v156, v38
	v_add_f32_e32 v36, v157, v37
	v_sub_f32_e32 v37, v45, v136
	v_exp_f32_e32 v159, v37
	v_sub_f32_e32 v37, v44, v136
	v_exp_f32_e32 v160, v37
	v_add_f32_e32 v36, v159, v36
	v_add_f32_e32 v36, v160, v36
	v_add_f32_e32 v190, v190, v36
	v_add_u32_e32 v138, 0xc5fc, v158
	ds_read2_b32 v[138:139], v138 offset1:1
	v_add_u32_e32 v140, 0xc5f4, v158
	ds_read2_b32 v[140:141], v140 offset1:1
	v_add_u32_e32 v136, 0xc5bc, v158
	ds_read2_b32 v[136:137], v136 offset1:1
	v_add_u32_e32 v142, 0xc5b4, v158
	ds_read2_b32 v[142:143], v142 offset1:1
	s_waitcnt lgkmcnt(3)
	v_fmamk_f32 v139, v28, 0x3e38aa3b, v139
	v_fmac_f32_e32 v138, 0x3e38aa3b, v29
	s_waitcnt lgkmcnt(2)
	v_fmamk_f32 v141, v30, 0x3e38aa3b, v141
	v_fmac_f32_e32 v140, 0x3e38aa3b, v31
	s_waitcnt lgkmcnt(1)
	v_fmamk_f32 v137, v20, 0x3e38aa3b, v137
	v_fmac_f32_e32 v136, 0x3e38aa3b, v21
	v_max3_f32 v20, v139, v138, v141
	v_max3_f32 v21, v140, v137, v136
	s_waitcnt lgkmcnt(0)
	v_fmamk_f32 v143, v22, 0x3e38aa3b, v143
	v_fmac_f32_e32 v142, 0x3e38aa3b, v23
	v_max_f32_e32 v22, v143, v142
	v_max3_f32 v20, v22, v20, v21
	v_cndmask_b32_e64 v20, v20, v225, s[36:37]
	v_add_f32_e32 v21, 0x41000000, v189
	v_cmp_gt_f32_e32 vcc, v20, v21
	s_cbranch_vccz .LBB0_475
	ds_bpermute_b32 v21, v233, v20
	v_max_f32_e32 v20, v20, v20
	s_waitcnt lgkmcnt(0)
	v_max_f32_e32 v21, v21, v21
	v_max_f32_e32 v20, v20, v21
	ds_bpermute_b32 v21, v234, v20
	s_waitcnt lgkmcnt(0)
	v_max3_f32 v161, v189, v20, v21
	v_sub_f32_e32 v20, v189, v161
	v_exp_f32_e32 v44, v20
	v_mov_b32_e32 v189, v161
	v_mul_f32_e32 v191, v191, v44
	v_pk_mul_f32 v[22:23], v[110:111], v[44:45] op_sel_hi:[1,0]
	v_pk_mul_f32 v[20:21], v[108:109], v[44:45] op_sel_hi:[1,0]
	v_pk_mul_f32 v[30:31], v[114:115], v[44:45] op_sel_hi:[1,0]
	v_pk_mul_f32 v[28:29], v[112:113], v[44:45] op_sel_hi:[1,0]
	v_pk_mul_f32 v[38:39], v[118:119], v[44:45] op_sel_hi:[1,0]
	v_pk_mul_f32 v[36:37], v[116:117], v[44:45] op_sel_hi:[1,0]
	v_pk_mul_f32 v[46:47], v[122:123], v[44:45] op_sel_hi:[1,0]
	v_pk_mul_f32 v[44:45], v[120:121], v[44:45] op_sel_hi:[1,0]
	s_branch .LBB0_476

; template <int MODE>
; __device__ __forceinline__ void nsa_compute(int cur, int buf, int t, int hl, u64 mymask, const bf16x8 (&Qf)[2][2], f32x4 (&O)[4][2], float (&m)[2], float (&l)[2],
;                                             const float (&inv)[2], float* impw, char* lds) {
;     ...
;       for (int kk = 0; kk < 2; ++kk)
; #pragma unroll
;         for (int e = 0; e < 4; ++e) {
;           const int off = 32 * s2 + 16 * kk + e;
;           int idx;
;           if (MODE <= 1) { idx = base - 16 * off; idx = idx > 0 ? idx : 0; } else idx = base - off;
;           sv[kk][e] = S[kk][r][e] * (0.125f * LOG2E) + tb[r * TS + idx];
;         }
;       float pv[2][4];
;       if (MODE == 1) {
; #pragma unroll
;         for (int kk = 0; kk < 2; ++kk)
; #pragma unroll
;           for (int e = 0; e < 4; ++e) pv[kk][e] = __builtin_amdgcn_exp2f(sv[kk][e] - m[r]) * inv[r];
; #pragma unroll
;         for (int kk = 0; kk < 2; ++kk) { g1s[kk] += pv[kk][0] + pv[kk][1] + pv[kk][2] + 0.5f * pv[kk][3]; p3s[kk] += 0.5f * pv[kk][3]; }
;       } else {
;         const float mxa = fmaxf(fmaxf(sv[0][0], sv[0][1]), sv[0][2]), mxb = fmaxf(fmaxf(sv[0][3], sv[1][0]), sv[1][1]);
;         float mx = fmaxf(fmaxf(fmaxf(sv[1][2], sv[1][3]), mxa), mxb);
;         if (MODE == 2) mx = selok ? mx : -__builtin_inff();
;         if (__any(mx > m[r] + 8.0f)) {
;           mx = fmaxf(mx, __shfl_xor(mx, 16)); mx = fmaxf(mx, __shfl_xor(mx, 32));
;           const float mn = fmaxf(m[r], mx), al = __builtin_amdgcn_exp2f(m[r] - mn);
;           m[r] = mn; l[r] *= al;
;           if (MODE != 0) {
; #pragma unroll
;             for (int df = 0; df < 4; ++df) O[df][r] *= al;
;           }
;         }
;         const float me = (MODE == 2) ? (selok ? m[r] : __builtin_inff()) : m[r];
;         float ps = 0.f;
; #pragma unroll
;         for (int kk = 0; kk < 2; ++kk)
; #pragma unroll
;           for (int e = 0; e < 4; ++e) { pv[kk][e] = __builtin_amdgcn_exp2f(sv[kk][e] - me); ps += pv[kk][e]; }
;         l[r] += ps;
.LBB0_479:
	v_cndmask_b32_e64 v165, v156, v228, s[36:37]
	v_sub_f32_e32 v151, v163, v165
	v_exp_f32_e32 v151, v151
	v_sub_f32_e32 v152, v152, v165
	v_exp_f32_e32 v152, v152
	v_sub_f32_e32 v153, v153, v165
	v_exp_f32_e32 v153, v153
	v_sub_f32_e32 v150, v150, v165
	v_exp_f32_e32 v150, v150
	v_add_f32_e32 v155, 0, v151
	v_add_f32_e32 v155, v152, v155
	v_add_f32_e32 v155, v153, v155
	v_sub_f32_e32 v149, v149, v165
	v_add_f32_e32 v156, v150, v155
	v_exp_f32_e32 v155, v149
	v_sub_f32_e32 v148, v148, v165
	v_add_f32_e32 v149, v155, v156
	v_exp_f32_e32 v156, v148
	s_nop 0
	v_add_f32_e32 v148, v156, v149
	v_sub_f32_e32 v149, v164, v165
	v_exp_f32_e32 v157, v149
	v_sub_f32_e32 v149, v154, v165
	v_exp_f32_e32 v154, v149
	v_add_f32_e32 v148, v157, v148
	v_add_f32_e32 v148, v154, v148
	v_add_f32_e32 v190, v190, v148
	v_add_u32_e32 v148, 0xc57c, v158
	ds_read2_b32 v[148:149], v148 offset1:1
	v_add_u32_e32 v222, 0xc574, v158
	ds_read2_b32 v[222:223], v222 offset1:1
	v_add_u32_e32 v230, 0xc53c, v158
	ds_read2_b32 v[230:231], v230 offset1:1
	v_add_u32_e32 v214, 0xc534, v158
	ds_read_b32 v213, v214 offset:4
	ds_read_b32 v214, v214
	s_waitcnt lgkmcnt(4)
	v_fmamk_f32 v149, v140, 0x3e38aa3b, v149
	v_fmac_f32_e32 v148, 0x3e38aa3b, v141
	s_waitcnt lgkmcnt(3)
	v_fmamk_f32 v141, v142, 0x3e38aa3b, v223
	v_fmamk_f32 v140, v143, 0x3e38aa3b, v222
	s_waitcnt lgkmcnt(2)
	v_fmamk_f32 v143, v136, 0x3e38aa3b, v231
	v_fmamk_f32 v142, v137, 0x3e38aa3b, v230
	s_waitcnt lgkmcnt(0)
	v_fmamk_f32 v158, v138, 0x3e38aa3b, v213
	v_fmamk_f32 v136, v139, 0x3e38aa3b, v214
	v_max3_f32 v137, v149, v148, v141
	v_max3_f32 v138, v140, v143, v142
	v_max_f32_e32 v139, v158, v136
	v_max3_f32 v137, v139, v137, v138
	v_cndmask_b32_e64 v137, v137, v225, s[36:37]
	v_add_f32_e32 v138, 0x41000000, v189
	v_cmp_gt_f32_e32 vcc, v137, v138
	s_cbranch_vccz .LBB0_481
	ds_bpermute_b32 v138, v233, v137
	v_max_f32_e32 v137, v137, v137
	s_waitcnt lgkmcnt(0)
	v_max_f32_e32 v138, v138, v138
	v_max_f32_e32 v137, v137, v138
	ds_bpermute_b32 v138, v234, v137
	s_waitcnt lgkmcnt(0)
	v_max3_f32 v137, v189, v137, v138
	v_sub_f32_e32 v138, v189, v137
	v_exp_f32_e32 v138, v138
	v_mov_b32_e32 v189, v137
	v_mul_f32_e32 v191, v191, v138
	v_pk_mul_f32 v[22:23], v[22:23], v[138:139] op_sel_hi:[1,0]
	v_pk_mul_f32 v[20:21], v[20:21], v[138:139] op_sel_hi:[1,0]
	v_pk_mul_f32 v[30:31], v[30:31], v[138:139] op_sel_hi:[1,0]
	v_pk_mul_f32 v[28:29], v[28:29], v[138:139] op_sel_hi:[1,0]
	v_pk_mul_f32 v[38:39], v[38:39], v[138:139] op_sel_hi:[1,0]
	v_pk_mul_f32 v[36:37], v[36:37], v[138:139] op_sel_hi:[1,0]
	v_pk_mul_f32 v[46:47], v[46:47], v[138:139] op_sel_hi:[1,0]
	v_pk_mul_f32 v[44:45], v[44:45], v[138:139] op_sel_hi:[1,0]
	s_branch .LBB0_482

; #define HBLK (opaque_tid() >> 8)
; __device__ __forceinline__ void run_phase(const Params& P, int ph, char* lds) {
;     ...
;       const int hb = HBLK;
;       for (int it = blockIdx.x * 2 + hb; it < 2048; it += gridDim.x * 2) mixB2_item(it, big, hsl, Pc, carryP, carryH, abuf);
.LBB0_498:
	v_xor_b32_e32 v222, 4, v212
	v_xor_b32_e32 v223, 2, v212
	v_mov_b32_e32 v230, 0xc00
	v_mov_b32_e32 v231, 0xfe0
	v_mov_b32_e32 v213, 0x3c088889
	v_mov_b32_e32 v214, 0x260
	v_mov_b32 v0, v179
	v_readlane_b32 s0, v253, 3
	v_ashrrev_i32_e32 v1, 8, v0
	s_nop 0
	v_add_u32_e32 v20, s0, v1
	s_movk_i32 s0, 0x800
	v_cmp_gt_i32_e32 vcc, s0, v20
	s_and_saveexec_b64 s[30:31], vcc
	s_cbranch_execz .LBB0_537
	v_lshrrev_b32_e32 v0, 8, v0
	v_readlane_b32 s0, v253, 3
	s_mov_b64 s[34:35], 0
	s_nop 0
	v_add_u16_e32 v21, s0, v0
